# P0 weight transposes: both 16-load passes of an item merged, 32 loads in flight, loop unrolled (on v67)
# baseline (speedup 1.0000x reference)
; #define LAS __attribute__((address_space(3)))
; __device__ __forceinline__ void tr_item(const float* W, int K, int N, bf16_t* WT, int ldt, int rowmode, const float* ksc, LAS float* scr, int item, int lane) {
;     const int nblk = N / 32, kb = item / nblk, nb = item % nblk, k0 = 64 * kb, n0 = 32 * nb;
; #pragma unroll 16
;     for (int i = 0; i < 32; ++i) { const int kk = 2 * i + (lane >> 5); float v = W[(size_t)(k0 + kk) * N + n0 + (lane & 31)]; if (ksc) v *= ksc[k0 + kk]; scr[kk * 33 + (lane & 31)] = v; }
.LBB0_25:
	v_lshl_add_u64 v[38:39], v[34:35], 0, s[18:19]
	global_load_dword v100, v[38:39], off
	v_lshl_add_u64 v[38:39], v[32:33], 0, s[18:19]
	global_load_dword v101, v[38:39], off
	v_lshl_add_u64 v[38:39], v[30:31], 0, s[18:19]
	global_load_dword v102, v[38:39], off
	v_lshl_add_u64 v[38:39], v[28:29], 0, s[18:19]
	global_load_dword v103, v[38:39], off
	v_lshl_add_u64 v[38:39], v[26:27], 0, s[18:19]
	global_load_dword v104, v[38:39], off
	v_lshl_add_u64 v[38:39], v[24:25], 0, s[18:19]
	global_load_dword v105, v[38:39], off
	v_lshl_add_u64 v[38:39], v[22:23], 0, s[18:19]
	global_load_dword v106, v[38:39], off
	v_lshl_add_u64 v[38:39], v[20:21], 0, s[18:19]
	global_load_dword v107, v[38:39], off
	v_lshl_add_u64 v[38:39], v[18:19], 0, s[18:19]
	global_load_dword v108, v[38:39], off
	v_lshl_add_u64 v[38:39], v[16:17], 0, s[18:19]
	global_load_dword v109, v[38:39], off
	v_lshl_add_u64 v[38:39], v[14:15], 0, s[18:19]
	global_load_dword v110, v[38:39], off
	v_lshl_add_u64 v[38:39], v[12:13], 0, s[18:19]
	global_load_dword v111, v[38:39], off
	v_lshl_add_u64 v[38:39], v[10:11], 0, s[18:19]
	global_load_dword v112, v[38:39], off
	v_lshl_add_u64 v[38:39], v[8:9], 0, s[18:19]
	global_load_dword v113, v[38:39], off
	v_lshl_add_u64 v[38:39], v[6:7], 0, s[18:19]
	global_load_dword v114, v[38:39], off
	v_lshl_add_u64 v[38:39], v[4:5], 0, s[18:19]
	s_add_u32 s18, s18, 0x20000
	s_addc_u32 s19, s19, 0
	s_cmp_lg_u32 s18, 0x40000
	global_load_dword v115, v[38:39], off
	v_lshl_add_u64 v[38:39], v[34:35], 0, s[18:19]
	global_load_dword v116, v[38:39], off
	v_lshl_add_u64 v[38:39], v[32:33], 0, s[18:19]
	global_load_dword v117, v[38:39], off
	v_lshl_add_u64 v[38:39], v[30:31], 0, s[18:19]
	global_load_dword v118, v[38:39], off
	v_lshl_add_u64 v[38:39], v[28:29], 0, s[18:19]
	global_load_dword v119, v[38:39], off
	v_lshl_add_u64 v[38:39], v[26:27], 0, s[18:19]
	global_load_dword v120, v[38:39], off
	v_lshl_add_u64 v[38:39], v[24:25], 0, s[18:19]
	global_load_dword v121, v[38:39], off
	v_lshl_add_u64 v[38:39], v[22:23], 0, s[18:19]
	global_load_dword v122, v[38:39], off
	v_lshl_add_u64 v[38:39], v[20:21], 0, s[18:19]
	global_load_dword v123, v[38:39], off
	v_lshl_add_u64 v[38:39], v[18:19], 0, s[18:19]
	global_load_dword v124, v[38:39], off
	v_lshl_add_u64 v[38:39], v[16:17], 0, s[18:19]
	global_load_dword v125, v[38:39], off
	v_lshl_add_u64 v[38:39], v[14:15], 0, s[18:19]
	global_load_dword v126, v[38:39], off
	v_lshl_add_u64 v[38:39], v[12:13], 0, s[18:19]
	global_load_dword v127, v[38:39], off
	v_lshl_add_u64 v[38:39], v[10:11], 0, s[18:19]
	global_load_dword v128, v[38:39], off
	v_lshl_add_u64 v[38:39], v[8:9], 0, s[18:19]
	global_load_dword v129, v[38:39], off
	v_lshl_add_u64 v[38:39], v[6:7], 0, s[18:19]
	global_load_dword v130, v[38:39], off
	v_lshl_add_u64 v[38:39], v[4:5], 0, s[18:19]
	s_add_u32 s18, s18, 0x20000
	s_addc_u32 s19, s19, 0
	s_cmp_lg_u32 s18, 0x40000
	global_load_dword v131, v[38:39], off
	s_waitcnt vmcnt(31)
	ds_write_b32 v36, v100
	s_waitcnt vmcnt(30)
	ds_write_b32 v36, v101 offset:264
	s_waitcnt vmcnt(29)
	ds_write_b32 v36, v102 offset:528
	s_waitcnt vmcnt(28)
	ds_write_b32 v36, v103 offset:792
	s_waitcnt vmcnt(27)
	ds_write_b32 v36, v104 offset:1056
	s_waitcnt vmcnt(26)
	ds_write_b32 v36, v105 offset:1320
	s_waitcnt vmcnt(25)
	ds_write_b32 v36, v106 offset:1584
	s_waitcnt vmcnt(24)
	ds_write_b32 v36, v107 offset:1848
	s_waitcnt vmcnt(23)
	ds_write_b32 v36, v108 offset:2112
	s_waitcnt vmcnt(22)
	ds_write_b32 v36, v109 offset:2376
	s_waitcnt vmcnt(21)
	ds_write_b32 v36, v110 offset:2640
	s_waitcnt vmcnt(20)
	ds_write_b32 v36, v111 offset:2904
	s_waitcnt vmcnt(19)
; #define LAS __attribute__((address_space(3)))
; __device__ __forceinline__ unsigned pk2(float lo, float hi) { f32x2 v = {lo, hi}; bf16x2_t b = __builtin_convertvector(v, bf16x2_t); return __builtin_bit_cast(unsigned, b); }
; __device__ __forceinline__ void tr_item(const float* W, int K, int N, bf16_t* WT, int ldt, int rowmode, const float* ksc, LAS float* scr, int item, int lane) {
;     ...
;     for (int i = 0; i < 32; ++i) { const int kk = 2 * i + (lane >> 5); float v = W[(size_t)(k0 + kk) * N + n0 + (lane & 31)]; if (ksc) v *= ksc[k0 + kk]; scr[kk * 33 + (lane & 31)] = v; }
;     asm volatile("s_waitcnt lgkmcnt(0)" ::: "memory");
;     const int c = lane & 7;
; #pragma unroll
;     for (int j = 0; j < 4; ++j) { const int n = n0 + (lane >> 3) + 8 * j; const LAS float* s = scr + (8 * c) * 33 + (lane >> 3) + 8 * j;
;         u32x4 o; o.x = pk2(s[0 * 33], s[1 * 33]); o.y = pk2(s[2 * 33], s[3 * 33]); o.z = pk2(s[4 * 33], s[5 * 33]); o.w = pk2(s[6 * 33], s[7 * 33]);
;         int row = n; if (rowmode) row = (n >> 7) * 256 + (n & 127) + (rowmode == 2 ? 128 : 0);
;         *(u32x4*)(WT + (size_t)row * ldt + k0 + 8 * c) = o; }
	ds_write_b32 v36, v112 offset:3168
	s_waitcnt vmcnt(18)
	ds_write_b32 v36, v113 offset:3432
	s_waitcnt vmcnt(17)
	ds_write_b32 v36, v114 offset:3696
	s_waitcnt vmcnt(16)
	ds_write_b32 v36, v115 offset:3960
	v_add_u32_e32 v36, 0x1080, v36
	s_waitcnt vmcnt(15)
	ds_write_b32 v36, v116
	s_waitcnt vmcnt(14)
	ds_write_b32 v36, v117 offset:264
	s_waitcnt vmcnt(13)
	ds_write_b32 v36, v118 offset:528
	s_waitcnt vmcnt(12)
	ds_write_b32 v36, v119 offset:792
	s_waitcnt vmcnt(11)
	ds_write_b32 v36, v120 offset:1056
	s_waitcnt vmcnt(10)
	ds_write_b32 v36, v121 offset:1320
	s_waitcnt vmcnt(9)
	ds_write_b32 v36, v122 offset:1584
	s_waitcnt vmcnt(8)
	ds_write_b32 v36, v123 offset:1848
	s_waitcnt vmcnt(7)
	ds_write_b32 v36, v124 offset:2112
	s_waitcnt vmcnt(6)
	ds_write_b32 v36, v125 offset:2376
	s_waitcnt vmcnt(5)
	ds_write_b32 v36, v126 offset:2640
	s_waitcnt vmcnt(4)
	ds_write_b32 v36, v127 offset:2904
	s_waitcnt vmcnt(3)
	ds_write_b32 v36, v128 offset:3168
	s_waitcnt vmcnt(2)
	ds_write_b32 v36, v129 offset:3432
	s_waitcnt vmcnt(1)
	ds_write_b32 v36, v130 offset:3696
	s_waitcnt vmcnt(0)
	ds_write_b32 v36, v131 offset:3960
	v_add_u32_e32 v36, 0x1080, v36
	v_ashrrev_i32_e32 v4, 3, v2
	v_lshlrev_b32_e32 v2, 3, v2
	v_and_b32_e32 v2, 56, v2
	s_and_b64 s[4:5], s[4:5], exec
	v_add_u32_e32 v28, s10, v4
	v_mul_u32_u24_e32 v5, 0x84, v2
	v_lshlrev_b32_e32 v4, 2, v4
	s_cselect_b32 s4, 0x580000, 0
	s_waitcnt lgkmcnt(0)
	v_add3_u32 v29, s3, v5, v4
	s_add_u32 s11, s38, s4
	ds_read2_b32 v[8:9], v29 offset0:33 offset1:41
	ds_read2_b32 v[10:11], v29 offset1:8
	ds_read2_b32 v[12:13], v29 offset0:66 offset1:74
	ds_read2_b32 v[14:15], v29 offset0:99 offset1:107
	ds_read2_b32 v[16:17], v29 offset0:132 offset1:140
	ds_read2_b32 v[18:19], v29 offset0:165 offset1:173
	ds_read2_b32 v[20:21], v29 offset0:198 offset1:206
	ds_read2_b32 v[22:23], v29 offset0:231 offset1:239
	s_addc_u32 s14, s39, 0
	s_lshl_b64 s[4:5], s[8:9], 1
	s_add_u32 s4, s11, s4
	s_addc_u32 s5, s14, s5
	v_lshlrev_b32_e32 v2, 1, v2
	v_lshl_add_u64 v[24:25], s[4:5], 0, v[2:3]
	s_waitcnt lgkmcnt(6)
	v_cvt_pk_bf16_f32 v4, v10, v8
	s_waitcnt lgkmcnt(4)
	v_cvt_pk_bf16_f32 v5, v12, v14
	s_waitcnt lgkmcnt(2)
	v_cvt_pk_bf16_f32 v6, v16, v18
	s_waitcnt lgkmcnt(0)
	v_cvt_pk_bf16_f32 v7, v20, v22
	v_mad_i64_i32 v[26:27], s[4:5], v28, s56, v[24:25]
	v_add_u32_e32 v2, 8, v28
	global_store_dwordx4 v[26:27], v[4:7], off
	s_nop 1
	v_cvt_pk_bf16_f32 v4, v11, v9
	v_cvt_pk_bf16_f32 v5, v13, v15
	v_cvt_pk_bf16_f32 v6, v17, v19
	v_cvt_pk_bf16_f32 v7, v21, v23
	v_mad_i64_i32 v[8:9], s[4:5], v2, s56, v[24:25]
	global_store_dwordx4 v[8:9], v[4:7], off
	ds_read2_b32 v[8:9], v29 offset0:49 offset1:57
	ds_read2_b32 v[10:11], v29 offset0:16 offset1:24
	ds_read2_b32 v[12:13], v29 offset0:82 offset1:90
	ds_read2_b32 v[14:15], v29 offset0:115 offset1:123
	ds_read2_b32 v[16:17], v29 offset0:148 offset1:156
	ds_read2_b32 v[18:19], v29 offset0:181 offset1:189
	ds_read2_b32 v[20:21], v29 offset0:214 offset1:222
	ds_read2_b32 v[22:23], v29 offset0:247 offset1:255
	v_add_u32_e32 v2, 16, v28
	s_waitcnt lgkmcnt(6)
	v_cvt_pk_bf16_f32 v4, v10, v8
	s_waitcnt lgkmcnt(4)
	v_cvt_pk_bf16_f32 v5, v12, v14
	s_waitcnt lgkmcnt(2)
	v_cvt_pk_bf16_f32 v6, v16, v18
	s_waitcnt lgkmcnt(0)
	v_cvt_pk_bf16_f32 v7, v20, v22
	v_mad_i64_i32 v[26:27], s[4:5], v2, s56, v[24:25]
	v_add_u32_e32 v2, 24, v28
	global_store_dwordx4 v[26:27], v[4:7], off
	s_nop 1
	v_cvt_pk_bf16_f32 v4, v11, v9
	v_cvt_pk_bf16_f32 v5, v13, v15
	v_cvt_pk_bf16_f32 v6, v17, v19
	v_cvt_pk_bf16_f32 v7, v21, v23
	v_mad_i64_i32 v[8:9], s[4:5], v2, s56, v[24:25]
	global_store_dwordx4 v[8:9], v[4:7], off
	s_waitcnt lgkmcnt(0)
	s_mov_b64 s[4:5], 0

; #define LAS __attribute__((address_space(3)))
; __device__ __forceinline__ void tr_item(const float* W, int K, int N, bf16_t* WT, int ldt, int rowmode, const float* ksc, LAS float* scr, int item, int lane) {
;     const int nblk = N / 32, kb = item / nblk, nb = item % nblk, k0 = 64 * kb, n0 = 32 * nb;
; #pragma unroll 16
;     for (int i = 0; i < 32; ++i) { const int kk = 2 * i + (lane >> 5); float v = W[(size_t)(k0 + kk) * N + n0 + (lane & 31)]; if (ksc) v *= ksc[k0 + kk]; scr[kk * 33 + (lane & 31)] = v; }
.LBB0_29:
	v_lshl_add_u64 v[38:39], v[34:35], 0, s[10:11]
	global_load_dword v100, v[38:39], off
	v_lshl_add_u64 v[38:39], v[32:33], 0, s[10:11]
	global_load_dword v101, v[38:39], off
	v_lshl_add_u64 v[38:39], v[30:31], 0, s[10:11]
	global_load_dword v102, v[38:39], off
	v_lshl_add_u64 v[38:39], v[28:29], 0, s[10:11]
	global_load_dword v103, v[38:39], off
	v_lshl_add_u64 v[38:39], v[26:27], 0, s[10:11]
	global_load_dword v104, v[38:39], off
	v_lshl_add_u64 v[38:39], v[24:25], 0, s[10:11]
	global_load_dword v105, v[38:39], off
	v_lshl_add_u64 v[38:39], v[22:23], 0, s[10:11]
	global_load_dword v106, v[38:39], off
	v_lshl_add_u64 v[38:39], v[20:21], 0, s[10:11]
	global_load_dword v107, v[38:39], off
	v_lshl_add_u64 v[38:39], v[18:19], 0, s[10:11]
	global_load_dword v108, v[38:39], off
	v_lshl_add_u64 v[38:39], v[16:17], 0, s[10:11]
	global_load_dword v109, v[38:39], off
	v_lshl_add_u64 v[38:39], v[14:15], 0, s[10:11]
	global_load_dword v110, v[38:39], off
	v_lshl_add_u64 v[38:39], v[12:13], 0, s[10:11]
	global_load_dword v111, v[38:39], off
	v_lshl_add_u64 v[38:39], v[10:11], 0, s[10:11]
	global_load_dword v112, v[38:39], off
	v_lshl_add_u64 v[38:39], v[8:9], 0, s[10:11]
	global_load_dword v113, v[38:39], off
	v_lshl_add_u64 v[38:39], v[6:7], 0, s[10:11]
	global_load_dword v114, v[38:39], off
	v_lshl_add_u64 v[38:39], v[4:5], 0, s[10:11]
	s_add_u32 s10, s10, 0x58000
	s_addc_u32 s11, s11, 0
	s_cmp_lg_u32 s10, 0xb0000
	global_load_dword v115, v[38:39], off
	v_lshl_add_u64 v[38:39], v[34:35], 0, s[10:11]
	global_load_dword v116, v[38:39], off
	v_lshl_add_u64 v[38:39], v[32:33], 0, s[10:11]
	global_load_dword v117, v[38:39], off
	v_lshl_add_u64 v[38:39], v[30:31], 0, s[10:11]
	global_load_dword v118, v[38:39], off
	v_lshl_add_u64 v[38:39], v[28:29], 0, s[10:11]
	global_load_dword v119, v[38:39], off
	v_lshl_add_u64 v[38:39], v[26:27], 0, s[10:11]
	global_load_dword v120, v[38:39], off
	v_lshl_add_u64 v[38:39], v[24:25], 0, s[10:11]
	global_load_dword v121, v[38:39], off
	v_lshl_add_u64 v[38:39], v[22:23], 0, s[10:11]
	global_load_dword v122, v[38:39], off
	v_lshl_add_u64 v[38:39], v[20:21], 0, s[10:11]
	global_load_dword v123, v[38:39], off
	v_lshl_add_u64 v[38:39], v[18:19], 0, s[10:11]
	global_load_dword v124, v[38:39], off
	v_lshl_add_u64 v[38:39], v[16:17], 0, s[10:11]
	global_load_dword v125, v[38:39], off
	v_lshl_add_u64 v[38:39], v[14:15], 0, s[10:11]
	global_load_dword v126, v[38:39], off
	v_lshl_add_u64 v[38:39], v[12:13], 0, s[10:11]
	global_load_dword v127, v[38:39], off
	v_lshl_add_u64 v[38:39], v[10:11], 0, s[10:11]
	global_load_dword v128, v[38:39], off
	v_lshl_add_u64 v[38:39], v[8:9], 0, s[10:11]
	global_load_dword v129, v[38:39], off
	v_lshl_add_u64 v[38:39], v[6:7], 0, s[10:11]
	global_load_dword v130, v[38:39], off
	v_lshl_add_u64 v[38:39], v[4:5], 0, s[10:11]
	s_add_u32 s10, s10, 0x58000
	s_addc_u32 s11, s11, 0
	s_cmp_lg_u32 s10, 0xb0000
	global_load_dword v131, v[38:39], off
	s_waitcnt vmcnt(31)
	ds_write_b32 v36, v100
	s_waitcnt vmcnt(30)
	ds_write_b32 v36, v101 offset:264
	s_waitcnt vmcnt(29)
	ds_write_b32 v36, v102 offset:528
	s_waitcnt vmcnt(28)
	ds_write_b32 v36, v103 offset:792
	s_waitcnt vmcnt(27)
	ds_write_b32 v36, v104 offset:1056
	s_waitcnt vmcnt(26)
	ds_write_b32 v36, v105 offset:1320
	s_waitcnt vmcnt(25)
	ds_write_b32 v36, v106 offset:1584
	s_waitcnt vmcnt(24)
	ds_write_b32 v36, v107 offset:1848
	s_waitcnt vmcnt(23)
	ds_write_b32 v36, v108 offset:2112
	s_waitcnt vmcnt(22)
	ds_write_b32 v36, v109 offset:2376
	s_waitcnt vmcnt(21)
	ds_write_b32 v36, v110 offset:2640
	s_waitcnt vmcnt(20)
	ds_write_b32 v36, v111 offset:2904
	s_waitcnt vmcnt(19)
	ds_write_b32 v36, v112 offset:3168
	s_waitcnt vmcnt(18)
	ds_write_b32 v36, v113 offset:3432
	s_waitcnt vmcnt(17)
	ds_write_b32 v36, v114 offset:3696
	s_waitcnt vmcnt(16)
	ds_write_b32 v36, v115 offset:3960
	v_add_u32_e32 v36, 0x1080, v36
	s_waitcnt vmcnt(15)
	ds_write_b32 v36, v116
	s_waitcnt vmcnt(14)
	ds_write_b32 v36, v117 offset:264
	s_waitcnt vmcnt(13)
; #define LAS __attribute__((address_space(3)))
; __device__ __forceinline__ unsigned pk2(float lo, float hi) { f32x2 v = {lo, hi}; bf16x2_t b = __builtin_convertvector(v, bf16x2_t); return __builtin_bit_cast(unsigned, b); }
; __device__ __forceinline__ void tr_item(const float* W, int K, int N, bf16_t* WT, int ldt, int rowmode, const float* ksc, LAS float* scr, int item, int lane) {
;     ...
;     for (int i = 0; i < 32; ++i) { const int kk = 2 * i + (lane >> 5); float v = W[(size_t)(k0 + kk) * N + n0 + (lane & 31)]; if (ksc) v *= ksc[k0 + kk]; scr[kk * 33 + (lane & 31)] = v; }
;     asm volatile("s_waitcnt lgkmcnt(0)" ::: "memory");
;     const int c = lane & 7;
; #pragma unroll
;     for (int j = 0; j < 4; ++j) { const int n = n0 + (lane >> 3) + 8 * j; const LAS float* s = scr + (8 * c) * 33 + (lane >> 3) + 8 * j;
;         u32x4 o; o.x = pk2(s[0 * 33], s[1 * 33]); o.y = pk2(s[2 * 33], s[3 * 33]); o.z = pk2(s[4 * 33], s[5 * 33]); o.w = pk2(s[6 * 33], s[7 * 33]);
;         int row = n; if (rowmode) row = (n >> 7) * 256 + (n & 127) + (rowmode == 2 ? 128 : 0);
;         *(u32x4*)(WT + (size_t)row * ldt + k0 + 8 * c) = o; }
	ds_write_b32 v36, v118 offset:528
	s_waitcnt vmcnt(12)
	ds_write_b32 v36, v119 offset:792
	s_waitcnt vmcnt(11)
	ds_write_b32 v36, v120 offset:1056
	s_waitcnt vmcnt(10)
	ds_write_b32 v36, v121 offset:1320
	s_waitcnt vmcnt(9)
	ds_write_b32 v36, v122 offset:1584
	s_waitcnt vmcnt(8)
	ds_write_b32 v36, v123 offset:1848
	s_waitcnt vmcnt(7)
	ds_write_b32 v36, v124 offset:2112
	s_waitcnt vmcnt(6)
	ds_write_b32 v36, v125 offset:2376
	s_waitcnt vmcnt(5)
	ds_write_b32 v36, v126 offset:2640
	s_waitcnt vmcnt(4)
	ds_write_b32 v36, v127 offset:2904
	s_waitcnt vmcnt(3)
	ds_write_b32 v36, v128 offset:3168
	s_waitcnt vmcnt(2)
	ds_write_b32 v36, v129 offset:3432
	s_waitcnt vmcnt(1)
	ds_write_b32 v36, v130 offset:3696
	s_waitcnt vmcnt(0)
	ds_write_b32 v36, v131 offset:3960
	v_add_u32_e32 v36, 0x1080, v36
	s_lshr_b32 s9, s18, 1
	s_mul_i32 s9, s9, 0xb00000
	s_add_u32 s9, s36, s9
	v_ashrrev_i32_e32 v4, 3, v2
	v_lshlrev_b32_e32 v2, 3, v2
	s_addc_u32 s10, s37, 0
	v_add_u32_e32 v28, s8, v4
	v_and_b32_e32 v2, 56, v2
	s_lshl_b32 s8, s14, 7
	s_lshl_b64 s[4:5], s[4:5], 1
	v_mul_u32_u24_e32 v5, 0x84, v2
	v_lshlrev_b32_e32 v4, 2, v4
	s_add_u32 s4, s9, s4
	s_waitcnt lgkmcnt(0)
	v_add3_u32 v29, s3, v5, v4
	s_addc_u32 s5, s10, s5
	v_lshlrev_b32_e32 v2, 1, v2
	ds_read2_b32 v[8:9], v29 offset0:33 offset1:41
	ds_read2_b32 v[10:11], v29 offset1:8
	ds_read2_b32 v[12:13], v29 offset0:66 offset1:74
	ds_read2_b32 v[14:15], v29 offset0:99 offset1:107
	ds_read2_b32 v[16:17], v29 offset0:132 offset1:140
	ds_read2_b32 v[18:19], v29 offset0:165 offset1:173
	ds_read2_b32 v[20:21], v29 offset0:198 offset1:206
	ds_read2_b32 v[22:23], v29 offset0:231 offset1:239
	v_lshl_add_u64 v[24:25], s[4:5], 0, v[2:3]
	v_lshlrev_b32_e32 v2, 1, v28
	s_waitcnt lgkmcnt(6)
	v_cvt_pk_bf16_f32 v4, v10, v8
	v_and_b32_e32 v2, 0xffffff00, v2
	v_and_b32_e32 v8, 0x7f, v28
	v_or3_b32 v26, v8, v2, s8
	v_add_u32_e32 v2, 8, v28
	v_ashrrev_i32_e32 v27, 31, v26
	v_lshlrev_b32_e32 v8, 1, v2
	v_lshlrev_b64 v[26:27], 11, v[26:27]
	v_and_b32_e32 v8, 0xffffff00, v8
	v_and_b32_e32 v2, 0x7f, v2
	s_waitcnt lgkmcnt(4)
	v_cvt_pk_bf16_f32 v5, v12, v14
	s_waitcnt lgkmcnt(2)
	v_cvt_pk_bf16_f32 v6, v16, v18
	s_waitcnt lgkmcnt(0)
	v_cvt_pk_bf16_f32 v7, v20, v22
	v_lshl_add_u64 v[26:27], v[24:25], 0, v[26:27]
	v_or3_b32 v8, v2, v8, s8
	global_store_dwordx4 v[26:27], v[4:7], off
	v_add_u32_e32 v2, 16, v28
	s_nop 0
	v_cvt_pk_bf16_f32 v4, v11, v9
	v_ashrrev_i32_e32 v9, 31, v8
	v_lshlrev_b64 v[8:9], 11, v[8:9]
	v_cvt_pk_bf16_f32 v5, v13, v15
	v_cvt_pk_bf16_f32 v6, v17, v19
	v_cvt_pk_bf16_f32 v7, v21, v23
	v_lshl_add_u64 v[8:9], v[24:25], 0, v[8:9]
	global_store_dwordx4 v[8:9], v[4:7], off
	ds_read2_b32 v[8:9], v29 offset0:16 offset1:24
	ds_read2_b32 v[10:11], v29 offset0:49 offset1:57
	ds_read2_b32 v[12:13], v29 offset0:82 offset1:90
	ds_read2_b32 v[14:15], v29 offset0:115 offset1:123
	ds_read2_b32 v[16:17], v29 offset0:148 offset1:156
	ds_read2_b32 v[18:19], v29 offset0:181 offset1:189
	ds_read2_b32 v[20:21], v29 offset0:214 offset1:222
	ds_read2_b32 v[22:23], v29 offset0:247 offset1:255
	s_waitcnt lgkmcnt(6)
	v_cvt_pk_bf16_f32 v4, v8, v10
	v_lshlrev_b32_e32 v8, 1, v2
	v_and_b32_e32 v8, 0xffffff00, v8
	v_and_b32_e32 v2, 0x7f, v2
	v_or3_b32 v26, v2, v8, s8
	v_add_u32_e32 v2, 24, v28
	v_ashrrev_i32_e32 v27, 31, v26
	v_lshlrev_b32_e32 v8, 1, v2
	v_lshlrev_b64 v[26:27], 11, v[26:27]
	v_and_b32_e32 v8, 0xffffff00, v8
	v_and_b32_e32 v2, 0x7f, v2
	s_waitcnt lgkmcnt(4)
	v_cvt_pk_bf16_f32 v5, v12, v14
	s_waitcnt lgkmcnt(2)
	v_cvt_pk_bf16_f32 v6, v16, v18
	s_waitcnt lgkmcnt(0)
	v_cvt_pk_bf16_f32 v7, v20, v22
	v_lshl_add_u64 v[26:27], v[24:25], 0, v[26:27]
	v_or3_b32 v8, v2, v8, s8
	global_store_dwordx4 v[26:27], v[4:7], off
	s_nop 1
	v_cvt_pk_bf16_f32 v4, v9, v11
	v_ashrrev_i32_e32 v9, 31, v8
	v_lshlrev_b64 v[8:9], 11, v[8:9]
	v_cvt_pk_bf16_f32 v5, v13, v15
	v_cvt_pk_bf16_f32 v6, v17, v19
	v_cvt_pk_bf16_f32 v7, v21, v23
	v_lshl_add_u64 v[8:9], v[24:25], 0, v[8:9]
	global_store_dwordx4 v[8:9], v[4:7], off
	s_waitcnt lgkmcnt(0)

; #define LAS __attribute__((address_space(3)))
; __device__ __forceinline__ void tr_item(const float* W, int K, int N, bf16_t* WT, int ldt, int rowmode, const float* ksc, LAS float* scr, int item, int lane) {
;     const int nblk = N / 32, kb = item / nblk, nb = item % nblk, k0 = 64 * kb, n0 = 32 * nb;
; #pragma unroll 16
;     for (int i = 0; i < 32; ++i) { const int kk = 2 * i + (lane >> 5); float v = W[(size_t)(k0 + kk) * N + n0 + (lane & 31)]; if (ksc) v *= ksc[k0 + kk]; scr[kk * 33 + (lane & 31)] = v; }
.LBB0_34:
	v_lshl_add_u64 v[38:39], v[34:35], 0, s[4:5]
	global_load_dword v100, v[38:39], off
	v_lshl_add_u64 v[38:39], v[32:33], 0, s[4:5]
	global_load_dword v101, v[38:39], off
	v_lshl_add_u64 v[38:39], v[30:31], 0, s[4:5]
	global_load_dword v102, v[38:39], off
	v_lshl_add_u64 v[38:39], v[28:29], 0, s[4:5]
	global_load_dword v103, v[38:39], off
	v_lshl_add_u64 v[38:39], v[26:27], 0, s[4:5]
	global_load_dword v104, v[38:39], off
	v_lshl_add_u64 v[38:39], v[24:25], 0, s[4:5]
	global_load_dword v105, v[38:39], off
	v_lshl_add_u64 v[38:39], v[22:23], 0, s[4:5]
	global_load_dword v106, v[38:39], off
	v_lshl_add_u64 v[38:39], v[20:21], 0, s[4:5]
	global_load_dword v107, v[38:39], off
	v_lshl_add_u64 v[38:39], v[18:19], 0, s[4:5]
	global_load_dword v108, v[38:39], off
	v_lshl_add_u64 v[38:39], v[16:17], 0, s[4:5]
	global_load_dword v109, v[38:39], off
	v_lshl_add_u64 v[38:39], v[14:15], 0, s[4:5]
	global_load_dword v110, v[38:39], off
	v_lshl_add_u64 v[38:39], v[12:13], 0, s[4:5]
	global_load_dword v111, v[38:39], off
	v_lshl_add_u64 v[38:39], v[10:11], 0, s[4:5]
	global_load_dword v112, v[38:39], off
	v_lshl_add_u64 v[38:39], v[8:9], 0, s[4:5]
	global_load_dword v113, v[38:39], off
	v_lshl_add_u64 v[38:39], v[6:7], 0, s[4:5]
	global_load_dword v114, v[38:39], off
	v_lshl_add_u64 v[38:39], v[4:5], 0, s[4:5]
	s_add_u32 s4, s4, 0x20000
	s_addc_u32 s5, s5, 0
	s_cmp_lg_u32 s4, 0x40000
	global_load_dword v115, v[38:39], off
	v_lshl_add_u64 v[38:39], v[34:35], 0, s[4:5]
	global_load_dword v116, v[38:39], off
	v_lshl_add_u64 v[38:39], v[32:33], 0, s[4:5]
	global_load_dword v117, v[38:39], off
	v_lshl_add_u64 v[38:39], v[30:31], 0, s[4:5]
	global_load_dword v118, v[38:39], off
	v_lshl_add_u64 v[38:39], v[28:29], 0, s[4:5]
	global_load_dword v119, v[38:39], off
	v_lshl_add_u64 v[38:39], v[26:27], 0, s[4:5]
	global_load_dword v120, v[38:39], off
	v_lshl_add_u64 v[38:39], v[24:25], 0, s[4:5]
	global_load_dword v121, v[38:39], off
	v_lshl_add_u64 v[38:39], v[22:23], 0, s[4:5]
	global_load_dword v122, v[38:39], off
	v_lshl_add_u64 v[38:39], v[20:21], 0, s[4:5]
	global_load_dword v123, v[38:39], off
	v_lshl_add_u64 v[38:39], v[18:19], 0, s[4:5]
	global_load_dword v124, v[38:39], off
	v_lshl_add_u64 v[38:39], v[16:17], 0, s[4:5]
	global_load_dword v125, v[38:39], off
	v_lshl_add_u64 v[38:39], v[14:15], 0, s[4:5]
	global_load_dword v126, v[38:39], off
	v_lshl_add_u64 v[38:39], v[12:13], 0, s[4:5]
	global_load_dword v127, v[38:39], off
	v_lshl_add_u64 v[38:39], v[10:11], 0, s[4:5]
	global_load_dword v128, v[38:39], off
	v_lshl_add_u64 v[38:39], v[8:9], 0, s[4:5]
	global_load_dword v129, v[38:39], off
	v_lshl_add_u64 v[38:39], v[6:7], 0, s[4:5]
	global_load_dword v130, v[38:39], off
	v_lshl_add_u64 v[38:39], v[4:5], 0, s[4:5]
	s_add_u32 s4, s4, 0x20000
	s_addc_u32 s5, s5, 0
	s_cmp_lg_u32 s4, 0x40000
	global_load_dword v131, v[38:39], off
	s_waitcnt vmcnt(31)
	ds_write_b32 v37, v100
	s_waitcnt vmcnt(30)
	ds_write_b32 v37, v101 offset:264
	s_waitcnt vmcnt(29)
	ds_write_b32 v37, v102 offset:528
	s_waitcnt vmcnt(28)
	ds_write_b32 v37, v103 offset:792
	s_waitcnt vmcnt(27)
	ds_write_b32 v37, v104 offset:1056
	s_waitcnt vmcnt(26)
	ds_write_b32 v37, v105 offset:1320
	s_waitcnt vmcnt(25)
	ds_write_b32 v37, v106 offset:1584
	s_waitcnt vmcnt(24)
	ds_write_b32 v37, v107 offset:1848
	s_waitcnt vmcnt(23)
	ds_write_b32 v37, v108 offset:2112
	s_waitcnt vmcnt(22)
	ds_write_b32 v37, v109 offset:2376
	s_waitcnt vmcnt(21)
	ds_write_b32 v37, v110 offset:2640
	s_waitcnt vmcnt(20)
	ds_write_b32 v37, v111 offset:2904
	s_waitcnt vmcnt(19)
	ds_write_b32 v37, v112 offset:3168
	s_waitcnt vmcnt(18)
; #define LAS __attribute__((address_space(3)))
; __device__ __forceinline__ unsigned pk2(float lo, float hi) { f32x2 v = {lo, hi}; bf16x2_t b = __builtin_convertvector(v, bf16x2_t); return __builtin_bit_cast(unsigned, b); }
; __device__ __forceinline__ void tr_item(const float* W, int K, int N, bf16_t* WT, int ldt, int rowmode, const float* ksc, LAS float* scr, int item, int lane) {
;     ...
;     for (int i = 0; i < 32; ++i) { const int kk = 2 * i + (lane >> 5); float v = W[(size_t)(k0 + kk) * N + n0 + (lane & 31)]; if (ksc) v *= ksc[k0 + kk]; scr[kk * 33 + (lane & 31)] = v; }
;     asm volatile("s_waitcnt lgkmcnt(0)" ::: "memory");
;     const int c = lane & 7;
; #pragma unroll
;     for (int j = 0; j < 4; ++j) { const int n = n0 + (lane >> 3) + 8 * j; const LAS float* s = scr + (8 * c) * 33 + (lane >> 3) + 8 * j;
;         u32x4 o; o.x = pk2(s[0 * 33], s[1 * 33]); o.y = pk2(s[2 * 33], s[3 * 33]); o.z = pk2(s[4 * 33], s[5 * 33]); o.w = pk2(s[6 * 33], s[7 * 33]);
;         int row = n; if (rowmode) row = (n >> 7) * 256 + (n & 127) + (rowmode == 2 ? 128 : 0);
;         *(u32x4*)(WT + (size_t)row * ldt + k0 + 8 * c) = o; }
	ds_write_b32 v37, v113 offset:3432
	s_waitcnt vmcnt(17)
	ds_write_b32 v37, v114 offset:3696
	s_waitcnt vmcnt(16)
	ds_write_b32 v37, v115 offset:3960
	v_add_u32_e32 v37, 0x1080, v37
	s_waitcnt vmcnt(15)
	ds_write_b32 v37, v116
	s_waitcnt vmcnt(14)
	ds_write_b32 v37, v117 offset:264
	s_waitcnt vmcnt(13)
	ds_write_b32 v37, v118 offset:528
	s_waitcnt vmcnt(12)
	ds_write_b32 v37, v119 offset:792
	s_waitcnt vmcnt(11)
	ds_write_b32 v37, v120 offset:1056
	s_waitcnt vmcnt(10)
	ds_write_b32 v37, v121 offset:1320
	s_waitcnt vmcnt(9)
	ds_write_b32 v37, v122 offset:1584
	s_waitcnt vmcnt(8)
	ds_write_b32 v37, v123 offset:1848
	s_waitcnt vmcnt(7)
	ds_write_b32 v37, v124 offset:2112
	s_waitcnt vmcnt(6)
	ds_write_b32 v37, v125 offset:2376
	s_waitcnt vmcnt(5)
	ds_write_b32 v37, v126 offset:2640
	s_waitcnt vmcnt(4)
	ds_write_b32 v37, v127 offset:2904
	s_waitcnt vmcnt(3)
	ds_write_b32 v37, v128 offset:3168
	s_waitcnt vmcnt(2)
	ds_write_b32 v37, v129 offset:3432
	s_waitcnt vmcnt(1)
	ds_write_b32 v37, v130 offset:3696
	s_waitcnt vmcnt(0)
	ds_write_b32 v37, v131 offset:3960
	v_add_u32_e32 v37, 0x1080, v37
	s_lshl_b32 s5, s1, 5
	v_lshlrev_b32_e32 v4, 3, v36
	s_and_b32 s5, s5, 0x3e0
	v_ashrrev_i32_e32 v2, 3, v36
	v_and_b32_e32 v4, 56, v4
	s_lshl_b32 s4, s1, 1
	v_add_u32_e32 v8, s5, v2
	v_mul_u32_u24_e32 v5, 0x84, v4
	v_lshlrev_b32_e32 v2, 2, v2
	s_add_i32 s4, s4, 0x1e040
	s_waitcnt lgkmcnt(0)
	v_add3_u32 v28, s3, v5, v2
	s_and_b32 s4, s4, 0x1ffc0
	ds_read2_b32 v[10:11], v28 offset0:33 offset1:41
	ds_read2_b32 v[12:13], v28 offset1:8
	ds_read2_b32 v[14:15], v28 offset0:66 offset1:74
	ds_read2_b32 v[16:17], v28 offset0:99 offset1:107
	ds_read2_b32 v[18:19], v28 offset0:132 offset1:140
	ds_read2_b32 v[20:21], v28 offset0:165 offset1:173
	ds_read2_b32 v[22:23], v28 offset0:198 offset1:206
	ds_read2_b32 v[24:25], v28 offset0:231 offset1:239
	s_lshl_b32 s4, s4, 1
	s_add_u32 s4, s34, s4
	s_addc_u32 s5, s35, 0
	v_lshlrev_b32_e32 v2, 1, v4
	v_ashrrev_i32_e32 v9, 31, v8
	v_lshl_add_u64 v[26:27], s[4:5], 0, v[2:3]
	v_lshlrev_b64 v[8:9], 11, v[8:9]
	s_waitcnt lgkmcnt(6)
	v_cvt_pk_bf16_f32 v4, v12, v10
	s_waitcnt lgkmcnt(4)
	v_cvt_pk_bf16_f32 v5, v14, v16
	s_waitcnt lgkmcnt(2)
	v_cvt_pk_bf16_f32 v6, v18, v20
	s_waitcnt lgkmcnt(0)
	v_cvt_pk_bf16_f32 v7, v22, v24
	v_lshl_add_u64 v[8:9], v[26:27], 0, v[8:9]
	global_store_dwordx4 v[8:9], v[4:7], off
	v_add_co_u32_e32 v10, vcc, s59, v8
	s_nop 0
	v_cvt_pk_bf16_f32 v4, v13, v11
	v_cvt_pk_bf16_f32 v5, v15, v17
	v_cvt_pk_bf16_f32 v6, v19, v21
	v_cvt_pk_bf16_f32 v7, v23, v25
	ds_read2_b32 v[12:13], v28 offset0:49 offset1:57
	ds_read2_b32 v[14:15], v28 offset0:16 offset1:24
	ds_read2_b32 v[16:17], v28 offset0:82 offset1:90
	ds_read2_b32 v[18:19], v28 offset0:115 offset1:123
	ds_read2_b32 v[20:21], v28 offset0:148 offset1:156
	ds_read2_b32 v[22:23], v28 offset0:181 offset1:189
	ds_read2_b32 v[24:25], v28 offset0:214 offset1:222
	ds_read2_b32 v[26:27], v28 offset0:247 offset1:255
	v_addc_co_u32_e32 v11, vcc, 0, v9, vcc
	global_store_dwordx4 v[10:11], v[4:7], off
	v_add_co_u32_e32 v10, vcc, s60, v8
	s_waitcnt lgkmcnt(6)
	v_cvt_pk_bf16_f32 v4, v14, v12
	v_addc_co_u32_e32 v11, vcc, 0, v9, vcc
	s_waitcnt lgkmcnt(4)
	v_cvt_pk_bf16_f32 v5, v16, v18
	s_waitcnt lgkmcnt(2)
	v_cvt_pk_bf16_f32 v6, v20, v22
	s_waitcnt lgkmcnt(0)
	v_cvt_pk_bf16_f32 v7, v24, v26
	v_add_co_u32_e32 v8, vcc, 0xc000, v8
	global_store_dwordx4 v[10:11], v[4:7], off
	s_nop 0
	v_addc_co_u32_e32 v9, vcc, 0, v9, vcc
	v_cvt_pk_bf16_f32 v4, v15, v13
	v_cvt_pk_bf16_f32 v5, v17, v19
	v_cvt_pk_bf16_f32 v6, v21, v23
	v_cvt_pk_bf16_f32 v7, v25, v27
	global_store_dwordx4 v[8:9], v[4:7], off
	s_waitcnt lgkmcnt(0)

; #define LAS __attribute__((address_space(3)))
; __device__ __forceinline__ void tr_item(const float* W, int K, int N, bf16_t* WT, int ldt, int rowmode, const float* ksc, LAS float* scr, int item, int lane) {
;     const int nblk = N / 32, kb = item / nblk, nb = item % nblk, k0 = 64 * kb, n0 = 32 * nb;
; #pragma unroll 16
;     for (int i = 0; i < 32; ++i) { const int kk = 2 * i + (lane >> 5); float v = W[(size_t)(k0 + kk) * N + n0 + (lane & 31)]; if (ksc) v *= ksc[k0 + kk]; scr[kk * 33 + (lane & 31)] = v; }
.LBB0_39:
	v_lshl_add_u64 v[38:39], v[34:35], 0, s[4:5]
	global_load_dword v100, v[38:39], off
	v_lshl_add_u64 v[38:39], v[32:33], 0, s[4:5]
	global_load_dword v101, v[38:39], off
	v_lshl_add_u64 v[38:39], v[30:31], 0, s[4:5]
	global_load_dword v102, v[38:39], off
	v_lshl_add_u64 v[38:39], v[28:29], 0, s[4:5]
	global_load_dword v103, v[38:39], off
	v_lshl_add_u64 v[38:39], v[26:27], 0, s[4:5]
	global_load_dword v104, v[38:39], off
	v_lshl_add_u64 v[38:39], v[24:25], 0, s[4:5]
	global_load_dword v105, v[38:39], off
	v_lshl_add_u64 v[38:39], v[22:23], 0, s[4:5]
	global_load_dword v106, v[38:39], off
	v_lshl_add_u64 v[38:39], v[20:21], 0, s[4:5]
	global_load_dword v107, v[38:39], off
	v_lshl_add_u64 v[38:39], v[18:19], 0, s[4:5]
	global_load_dword v108, v[38:39], off
	v_lshl_add_u64 v[38:39], v[16:17], 0, s[4:5]
	global_load_dword v109, v[38:39], off
	v_lshl_add_u64 v[38:39], v[14:15], 0, s[4:5]
	global_load_dword v110, v[38:39], off
	v_lshl_add_u64 v[38:39], v[12:13], 0, s[4:5]
	global_load_dword v111, v[38:39], off
	v_lshl_add_u64 v[38:39], v[10:11], 0, s[4:5]
	global_load_dword v112, v[38:39], off
	v_lshl_add_u64 v[38:39], v[8:9], 0, s[4:5]
	global_load_dword v113, v[38:39], off
	v_lshl_add_u64 v[38:39], v[6:7], 0, s[4:5]
	global_load_dword v114, v[38:39], off
	v_lshl_add_u64 v[38:39], v[4:5], 0, s[4:5]
	s_add_u32 s4, s4, 0x80000
	s_addc_u32 s5, s5, 0
	s_cmp_lg_u32 s4, 0x100000
	global_load_dword v115, v[38:39], off
	v_lshl_add_u64 v[38:39], v[34:35], 0, s[4:5]
	global_load_dword v116, v[38:39], off
	v_lshl_add_u64 v[38:39], v[32:33], 0, s[4:5]
	global_load_dword v117, v[38:39], off
	v_lshl_add_u64 v[38:39], v[30:31], 0, s[4:5]
	global_load_dword v118, v[38:39], off
	v_lshl_add_u64 v[38:39], v[28:29], 0, s[4:5]
	global_load_dword v119, v[38:39], off
	v_lshl_add_u64 v[38:39], v[26:27], 0, s[4:5]
	global_load_dword v120, v[38:39], off
	v_lshl_add_u64 v[38:39], v[24:25], 0, s[4:5]
	global_load_dword v121, v[38:39], off
	v_lshl_add_u64 v[38:39], v[22:23], 0, s[4:5]
	global_load_dword v122, v[38:39], off
	v_lshl_add_u64 v[38:39], v[20:21], 0, s[4:5]
	global_load_dword v123, v[38:39], off
	v_lshl_add_u64 v[38:39], v[18:19], 0, s[4:5]
	global_load_dword v124, v[38:39], off
	v_lshl_add_u64 v[38:39], v[16:17], 0, s[4:5]
	global_load_dword v125, v[38:39], off
	v_lshl_add_u64 v[38:39], v[14:15], 0, s[4:5]
	global_load_dword v126, v[38:39], off
	v_lshl_add_u64 v[38:39], v[12:13], 0, s[4:5]
	global_load_dword v127, v[38:39], off
	v_lshl_add_u64 v[38:39], v[10:11], 0, s[4:5]
	global_load_dword v128, v[38:39], off
	v_lshl_add_u64 v[38:39], v[8:9], 0, s[4:5]
	global_load_dword v129, v[38:39], off
	v_lshl_add_u64 v[38:39], v[6:7], 0, s[4:5]
	global_load_dword v130, v[38:39], off
	v_lshl_add_u64 v[38:39], v[4:5], 0, s[4:5]
	s_add_u32 s4, s4, 0x80000
	s_addc_u32 s5, s5, 0
	s_cmp_lg_u32 s4, 0x100000
	global_load_dword v131, v[38:39], off
	s_waitcnt vmcnt(31)
	ds_write_b32 v36, v100
	s_waitcnt vmcnt(30)
	ds_write_b32 v36, v101 offset:264
	s_waitcnt vmcnt(29)
	ds_write_b32 v36, v102 offset:528
	s_waitcnt vmcnt(28)
	ds_write_b32 v36, v103 offset:792
	s_waitcnt vmcnt(27)
	ds_write_b32 v36, v104 offset:1056
	s_waitcnt vmcnt(26)
	ds_write_b32 v36, v105 offset:1320
	s_waitcnt vmcnt(25)
	ds_write_b32 v36, v106 offset:1584
	s_waitcnt vmcnt(24)
	ds_write_b32 v36, v107 offset:1848
	s_waitcnt vmcnt(23)
	ds_write_b32 v36, v108 offset:2112
	s_waitcnt vmcnt(22)
	ds_write_b32 v36, v109 offset:2376
	s_waitcnt vmcnt(21)
	ds_write_b32 v36, v110 offset:2640
	s_waitcnt vmcnt(20)
	ds_write_b32 v36, v111 offset:2904
	s_waitcnt vmcnt(19)
	ds_write_b32 v36, v112 offset:3168
	s_waitcnt vmcnt(18)
; #define LAS __attribute__((address_space(3)))
; __device__ __forceinline__ unsigned pk2(float lo, float hi) { f32x2 v = {lo, hi}; bf16x2_t b = __builtin_convertvector(v, bf16x2_t); return __builtin_bit_cast(unsigned, b); }
; __device__ __forceinline__ void tr_item(const float* W, int K, int N, bf16_t* WT, int ldt, int rowmode, const float* ksc, LAS float* scr, int item, int lane) {
;     ...
;     for (int i = 0; i < 32; ++i) { const int kk = 2 * i + (lane >> 5); float v = W[(size_t)(k0 + kk) * N + n0 + (lane & 31)]; if (ksc) v *= ksc[k0 + kk]; scr[kk * 33 + (lane & 31)] = v; }
;     asm volatile("s_waitcnt lgkmcnt(0)" ::: "memory");
;     const int c = lane & 7;
; #pragma unroll
;     for (int j = 0; j < 4; ++j) { const int n = n0 + (lane >> 3) + 8 * j; const LAS float* s = scr + (8 * c) * 33 + (lane >> 3) + 8 * j;
;         u32x4 o; o.x = pk2(s[0 * 33], s[1 * 33]); o.y = pk2(s[2 * 33], s[3 * 33]); o.z = pk2(s[4 * 33], s[5 * 33]); o.w = pk2(s[6 * 33], s[7 * 33]);
;         int row = n; if (rowmode) row = (n >> 7) * 256 + (n & 127) + (rowmode == 2 ? 128 : 0);
;         *(u32x4*)(WT + (size_t)row * ldt + k0 + 8 * c) = o; }
	ds_write_b32 v36, v113 offset:3432
	s_waitcnt vmcnt(17)
	ds_write_b32 v36, v114 offset:3696
	s_waitcnt vmcnt(16)
	ds_write_b32 v36, v115 offset:3960
	v_add_u32_e32 v36, 0x1080, v36
	s_waitcnt vmcnt(15)
	ds_write_b32 v36, v116
	s_waitcnt vmcnt(14)
	ds_write_b32 v36, v117 offset:264
	s_waitcnt vmcnt(13)
	ds_write_b32 v36, v118 offset:528
	s_waitcnt vmcnt(12)
	ds_write_b32 v36, v119 offset:792
	s_waitcnt vmcnt(11)
	ds_write_b32 v36, v120 offset:1056
	s_waitcnt vmcnt(10)
	ds_write_b32 v36, v121 offset:1320
	s_waitcnt vmcnt(9)
	ds_write_b32 v36, v122 offset:1584
	s_waitcnt vmcnt(8)
	ds_write_b32 v36, v123 offset:1848
	s_waitcnt vmcnt(7)
	ds_write_b32 v36, v124 offset:2112
	s_waitcnt vmcnt(6)
	ds_write_b32 v36, v125 offset:2376
	s_waitcnt vmcnt(5)
	ds_write_b32 v36, v126 offset:2640
	s_waitcnt vmcnt(4)
	ds_write_b32 v36, v127 offset:2904
	s_waitcnt vmcnt(3)
	ds_write_b32 v36, v128 offset:3168
	s_waitcnt vmcnt(2)
	ds_write_b32 v36, v129 offset:3432
	s_waitcnt vmcnt(1)
	ds_write_b32 v36, v130 offset:3696
	s_waitcnt vmcnt(0)
	ds_write_b32 v36, v131 offset:3960
	v_add_u32_e32 v36, 0x1080, v36
	s_add_i32 s4, s1, 0xfffff820
	s_lshl_b32 s5, s4, 5
	v_ashrrev_i32_e32 v4, 3, v2
	v_lshlrev_b32_e32 v2, 3, v2
	s_and_b32 s5, s5, 0xfe0
	v_and_b32_e32 v2, 56, v2
	v_add_u32_e32 v8, s5, v4
	v_mul_u32_u24_e32 v5, 0x84, v2
	v_lshlrev_b32_e32 v4, 2, v4
	s_waitcnt lgkmcnt(0)
	v_add3_u32 v28, s3, v5, v4
	ds_read2_b32 v[10:11], v28 offset0:33 offset1:41
	ds_read2_b32 v[12:13], v28 offset1:8
	ds_read2_b32 v[14:15], v28 offset0:66 offset1:74
	ds_read2_b32 v[16:17], v28 offset0:99 offset1:107
	ds_read2_b32 v[18:19], v28 offset0:132 offset1:140
	ds_read2_b32 v[20:21], v28 offset0:165 offset1:173
	ds_read2_b32 v[22:23], v28 offset0:198 offset1:206
	ds_read2_b32 v[24:25], v28 offset0:231 offset1:239
	s_and_b32 s4, s4, 0xff80
	s_add_u32 s4, s31, s4
	s_addc_u32 s5, s33, 0
	v_lshlrev_b32_e32 v2, 1, v2
	v_ashrrev_i32_e32 v9, 31, v8
	v_lshl_add_u64 v[26:27], s[4:5], 0, v[2:3]
	v_lshlrev_b64 v[8:9], 11, v[8:9]
	s_waitcnt lgkmcnt(6)
	v_cvt_pk_bf16_f32 v4, v12, v10
	s_waitcnt lgkmcnt(4)
	v_cvt_pk_bf16_f32 v5, v14, v16
	s_waitcnt lgkmcnt(2)
	v_cvt_pk_bf16_f32 v6, v18, v20
	s_waitcnt lgkmcnt(0)
	v_cvt_pk_bf16_f32 v7, v22, v24
	v_lshl_add_u64 v[8:9], v[26:27], 0, v[8:9]
	global_store_dwordx4 v[8:9], v[4:7], off
	v_add_co_u32_e32 v10, vcc, s59, v8
	s_nop 0
	v_cvt_pk_bf16_f32 v4, v13, v11
	v_cvt_pk_bf16_f32 v5, v15, v17
	v_cvt_pk_bf16_f32 v6, v19, v21
	v_cvt_pk_bf16_f32 v7, v23, v25
	ds_read2_b32 v[12:13], v28 offset0:49 offset1:57
	ds_read2_b32 v[14:15], v28 offset0:16 offset1:24
	ds_read2_b32 v[16:17], v28 offset0:82 offset1:90
	ds_read2_b32 v[18:19], v28 offset0:115 offset1:123
	ds_read2_b32 v[20:21], v28 offset0:148 offset1:156
	ds_read2_b32 v[22:23], v28 offset0:181 offset1:189
	ds_read2_b32 v[24:25], v28 offset0:214 offset1:222
	ds_read2_b32 v[26:27], v28 offset0:247 offset1:255
	v_addc_co_u32_e32 v11, vcc, 0, v9, vcc
	global_store_dwordx4 v[10:11], v[4:7], off
	v_add_co_u32_e32 v10, vcc, s60, v8
	s_waitcnt lgkmcnt(6)
	v_cvt_pk_bf16_f32 v4, v14, v12
	v_addc_co_u32_e32 v11, vcc, 0, v9, vcc
	s_waitcnt lgkmcnt(4)
	v_cvt_pk_bf16_f32 v5, v16, v18
	s_waitcnt lgkmcnt(2)
	v_cvt_pk_bf16_f32 v6, v20, v22
	s_waitcnt lgkmcnt(0)
	v_cvt_pk_bf16_f32 v7, v24, v26
	v_add_co_u32_e32 v8, vcc, 0xc000, v8
	global_store_dwordx4 v[10:11], v[4:7], off
	s_nop 0
	v_addc_co_u32_e32 v9, vcc, 0, v9, vcc
	v_cvt_pk_bf16_f32 v4, v15, v13
	v_cvt_pk_bf16_f32 v5, v17, v19
	v_cvt_pk_bf16_f32 v6, v21, v23
	v_cvt_pk_bf16_f32 v7, v25, v27
	global_store_dwordx4 v[8:9], v[4:7], off
	s_waitcnt lgkmcnt(0)

; #define LAS __attribute__((address_space(3)))
; __device__ __forceinline__ void tr_item(const float* W, int K, int N, bf16_t* WT, int ldt, int rowmode, const float* ksc, LAS float* scr, int item, int lane) {
;     const int nblk = N / 32, kb = item / nblk, nb = item % nblk, k0 = 64 * kb, n0 = 32 * nb;
; #pragma unroll 16
;     for (int i = 0; i < 32; ++i) { const int kk = 2 * i + (lane >> 5); float v = W[(size_t)(k0 + kk) * N + n0 + (lane & 31)]; if (ksc) v *= ksc[k0 + kk]; scr[kk * 33 + (lane & 31)] = v; }
.LBB0_44:
	v_lshl_add_u64 v[38:39], v[34:35], 0, s[4:5]
	global_load_dword v100, v[38:39], off
	v_lshl_add_u64 v[38:39], v[32:33], 0, s[4:5]
	global_load_dword v101, v[38:39], off
	v_lshl_add_u64 v[38:39], v[30:31], 0, s[4:5]
	global_load_dword v102, v[38:39], off
	v_lshl_add_u64 v[38:39], v[28:29], 0, s[4:5]
	global_load_dword v103, v[38:39], off
	v_lshl_add_u64 v[38:39], v[26:27], 0, s[4:5]
	global_load_dword v104, v[38:39], off
	v_lshl_add_u64 v[38:39], v[24:25], 0, s[4:5]
	global_load_dword v105, v[38:39], off
	v_lshl_add_u64 v[38:39], v[22:23], 0, s[4:5]
	global_load_dword v106, v[38:39], off
	v_lshl_add_u64 v[38:39], v[20:21], 0, s[4:5]
	global_load_dword v107, v[38:39], off
	v_lshl_add_u64 v[38:39], v[18:19], 0, s[4:5]
	global_load_dword v108, v[38:39], off
	v_lshl_add_u64 v[38:39], v[16:17], 0, s[4:5]
	global_load_dword v109, v[38:39], off
	v_lshl_add_u64 v[38:39], v[14:15], 0, s[4:5]
	global_load_dword v110, v[38:39], off
	v_lshl_add_u64 v[38:39], v[12:13], 0, s[4:5]
	global_load_dword v111, v[38:39], off
	v_lshl_add_u64 v[38:39], v[10:11], 0, s[4:5]
	global_load_dword v112, v[38:39], off
	v_lshl_add_u64 v[38:39], v[8:9], 0, s[4:5]
	global_load_dword v113, v[38:39], off
	v_lshl_add_u64 v[38:39], v[6:7], 0, s[4:5]
	global_load_dword v114, v[38:39], off
	v_lshl_add_u64 v[38:39], v[4:5], 0, s[4:5]
	s_add_u32 s4, s4, 0x20000
	s_addc_u32 s5, s5, 0
	s_cmp_lg_u32 s4, 0x40000
	global_load_dword v115, v[38:39], off
	v_lshl_add_u64 v[38:39], v[34:35], 0, s[4:5]
	global_load_dword v116, v[38:39], off
	v_lshl_add_u64 v[38:39], v[32:33], 0, s[4:5]
	global_load_dword v117, v[38:39], off
	v_lshl_add_u64 v[38:39], v[30:31], 0, s[4:5]
	global_load_dword v118, v[38:39], off
	v_lshl_add_u64 v[38:39], v[28:29], 0, s[4:5]
	global_load_dword v119, v[38:39], off
	v_lshl_add_u64 v[38:39], v[26:27], 0, s[4:5]
	global_load_dword v120, v[38:39], off
	v_lshl_add_u64 v[38:39], v[24:25], 0, s[4:5]
	global_load_dword v121, v[38:39], off
	v_lshl_add_u64 v[38:39], v[22:23], 0, s[4:5]
	global_load_dword v122, v[38:39], off
	v_lshl_add_u64 v[38:39], v[20:21], 0, s[4:5]
	global_load_dword v123, v[38:39], off
	v_lshl_add_u64 v[38:39], v[18:19], 0, s[4:5]
	global_load_dword v124, v[38:39], off
	v_lshl_add_u64 v[38:39], v[16:17], 0, s[4:5]
	global_load_dword v125, v[38:39], off
	v_lshl_add_u64 v[38:39], v[14:15], 0, s[4:5]
	global_load_dword v126, v[38:39], off
	v_lshl_add_u64 v[38:39], v[12:13], 0, s[4:5]
	global_load_dword v127, v[38:39], off
	v_lshl_add_u64 v[38:39], v[10:11], 0, s[4:5]
	global_load_dword v128, v[38:39], off
	v_lshl_add_u64 v[38:39], v[8:9], 0, s[4:5]
	global_load_dword v129, v[38:39], off
	v_lshl_add_u64 v[38:39], v[6:7], 0, s[4:5]
	global_load_dword v130, v[38:39], off
	v_lshl_add_u64 v[38:39], v[4:5], 0, s[4:5]
	s_add_u32 s4, s4, 0x20000
	s_addc_u32 s5, s5, 0
	s_cmp_lg_u32 s4, 0x40000
	global_load_dword v131, v[38:39], off
	s_waitcnt vmcnt(31)
	ds_write_b32 v37, v100
	s_waitcnt vmcnt(30)
	ds_write_b32 v37, v101 offset:264
	s_waitcnt vmcnt(29)
	ds_write_b32 v37, v102 offset:528
	s_waitcnt vmcnt(28)
	ds_write_b32 v37, v103 offset:792
	s_waitcnt vmcnt(27)
	ds_write_b32 v37, v104 offset:1056
	s_waitcnt vmcnt(26)
	ds_write_b32 v37, v105 offset:1320
	s_waitcnt vmcnt(25)
	ds_write_b32 v37, v106 offset:1584
	s_waitcnt vmcnt(24)
	ds_write_b32 v37, v107 offset:1848
	s_waitcnt vmcnt(23)
	ds_write_b32 v37, v108 offset:2112
	s_waitcnt vmcnt(22)
	ds_write_b32 v37, v109 offset:2376
	s_waitcnt vmcnt(21)
	ds_write_b32 v37, v110 offset:2640
	s_waitcnt vmcnt(20)
	ds_write_b32 v37, v111 offset:2904
	s_waitcnt vmcnt(19)
	ds_write_b32 v37, v112 offset:3168
	s_waitcnt vmcnt(18)
; #define LAS __attribute__((address_space(3)))
; __device__ __forceinline__ unsigned pk2(float lo, float hi) { f32x2 v = {lo, hi}; bf16x2_t b = __builtin_convertvector(v, bf16x2_t); return __builtin_bit_cast(unsigned, b); }
; __device__ __forceinline__ void tr_item(const float* W, int K, int N, bf16_t* WT, int ldt, int rowmode, const float* ksc, LAS float* scr, int item, int lane) {
;     ...
;     for (int i = 0; i < 32; ++i) { const int kk = 2 * i + (lane >> 5); float v = W[(size_t)(k0 + kk) * N + n0 + (lane & 31)]; if (ksc) v *= ksc[k0 + kk]; scr[kk * 33 + (lane & 31)] = v; }
;     asm volatile("s_waitcnt lgkmcnt(0)" ::: "memory");
;     const int c = lane & 7;
; #pragma unroll
;     for (int j = 0; j < 4; ++j) { const int n = n0 + (lane >> 3) + 8 * j; const LAS float* s = scr + (8 * c) * 33 + (lane >> 3) + 8 * j;
;         u32x4 o; o.x = pk2(s[0 * 33], s[1 * 33]); o.y = pk2(s[2 * 33], s[3 * 33]); o.z = pk2(s[4 * 33], s[5 * 33]); o.w = pk2(s[6 * 33], s[7 * 33]);
;         int row = n; if (rowmode) row = (n >> 7) * 256 + (n & 127) + (rowmode == 2 ? 128 : 0);
;         *(u32x4*)(WT + (size_t)row * ldt + k0 + 8 * c) = o; }
	ds_write_b32 v37, v113 offset:3432
	s_waitcnt vmcnt(17)
	ds_write_b32 v37, v114 offset:3696
	s_waitcnt vmcnt(16)
	ds_write_b32 v37, v115 offset:3960
	v_add_u32_e32 v37, 0x1080, v37
	s_waitcnt vmcnt(15)
	ds_write_b32 v37, v116
	s_waitcnt vmcnt(14)
	ds_write_b32 v37, v117 offset:264
	s_waitcnt vmcnt(13)
	ds_write_b32 v37, v118 offset:528
	s_waitcnt vmcnt(12)
	ds_write_b32 v37, v119 offset:792
	s_waitcnt vmcnt(11)
	ds_write_b32 v37, v120 offset:1056
	s_waitcnt vmcnt(10)
	ds_write_b32 v37, v121 offset:1320
	s_waitcnt vmcnt(9)
	ds_write_b32 v37, v122 offset:1584
	s_waitcnt vmcnt(8)
	ds_write_b32 v37, v123 offset:1848
	s_waitcnt vmcnt(7)
	ds_write_b32 v37, v124 offset:2112
	s_waitcnt vmcnt(6)
	ds_write_b32 v37, v125 offset:2376
	s_waitcnt vmcnt(5)
	ds_write_b32 v37, v126 offset:2640
	s_waitcnt vmcnt(4)
	ds_write_b32 v37, v127 offset:2904
	s_waitcnt vmcnt(3)
	ds_write_b32 v37, v128 offset:3168
	s_waitcnt vmcnt(2)
	ds_write_b32 v37, v129 offset:3432
	s_waitcnt vmcnt(1)
	ds_write_b32 v37, v130 offset:3696
	s_waitcnt vmcnt(0)
	ds_write_b32 v37, v131 offset:3960
	v_add_u32_e32 v37, 0x1080, v37
	s_lshl_b32 s5, s1, 5
	v_lshlrev_b32_e32 v4, 3, v36
	s_and_b32 s5, s5, 0x3e0
	v_ashrrev_i32_e32 v2, 3, v36
	v_and_b32_e32 v4, 56, v4
	s_lshl_b32 s4, s1, 1
	v_add_u32_e32 v8, s5, v2
	v_mul_u32_u24_e32 v5, 0x84, v4
	v_lshlrev_b32_e32 v2, 2, v2
	s_add_i32 s4, s4, 0x1f440
	s_waitcnt lgkmcnt(0)
	v_add3_u32 v28, s3, v5, v2
	s_and_b32 s4, s4, 0x1ffc0
	ds_read2_b32 v[10:11], v28 offset0:33 offset1:41
	ds_read2_b32 v[12:13], v28 offset1:8
	ds_read2_b32 v[14:15], v28 offset0:66 offset1:74
	ds_read2_b32 v[16:17], v28 offset0:99 offset1:107
	ds_read2_b32 v[18:19], v28 offset0:132 offset1:140
	ds_read2_b32 v[20:21], v28 offset0:165 offset1:173
	ds_read2_b32 v[22:23], v28 offset0:198 offset1:206
	ds_read2_b32 v[24:25], v28 offset0:231 offset1:239
	s_lshl_b32 s4, s4, 1
	s_add_u32 s4, s29, s4
	s_addc_u32 s5, s30, 0
	v_lshlrev_b32_e32 v2, 1, v4
	v_ashrrev_i32_e32 v9, 31, v8
	v_lshl_add_u64 v[26:27], s[4:5], 0, v[2:3]
	v_lshlrev_b64 v[8:9], 11, v[8:9]
	s_waitcnt lgkmcnt(6)
	v_cvt_pk_bf16_f32 v4, v12, v10
	s_waitcnt lgkmcnt(4)
	v_cvt_pk_bf16_f32 v5, v14, v16
	s_waitcnt lgkmcnt(2)
	v_cvt_pk_bf16_f32 v6, v18, v20
	s_waitcnt lgkmcnt(0)
	v_cvt_pk_bf16_f32 v7, v22, v24
	v_lshl_add_u64 v[8:9], v[26:27], 0, v[8:9]
	global_store_dwordx4 v[8:9], v[4:7], off
	v_add_co_u32_e32 v10, vcc, s59, v8
	s_nop 0
	v_cvt_pk_bf16_f32 v4, v13, v11
	v_cvt_pk_bf16_f32 v5, v15, v17
	v_cvt_pk_bf16_f32 v6, v19, v21
	v_cvt_pk_bf16_f32 v7, v23, v25
	ds_read2_b32 v[12:13], v28 offset0:49 offset1:57
	ds_read2_b32 v[14:15], v28 offset0:16 offset1:24
	ds_read2_b32 v[16:17], v28 offset0:82 offset1:90
	ds_read2_b32 v[18:19], v28 offset0:115 offset1:123
	ds_read2_b32 v[20:21], v28 offset0:148 offset1:156
	ds_read2_b32 v[22:23], v28 offset0:181 offset1:189
	ds_read2_b32 v[24:25], v28 offset0:214 offset1:222
	ds_read2_b32 v[26:27], v28 offset0:247 offset1:255
	v_addc_co_u32_e32 v11, vcc, 0, v9, vcc
	global_store_dwordx4 v[10:11], v[4:7], off
	v_add_co_u32_e32 v10, vcc, s60, v8
	s_waitcnt lgkmcnt(6)
	v_cvt_pk_bf16_f32 v4, v14, v12
	v_addc_co_u32_e32 v11, vcc, 0, v9, vcc
	s_waitcnt lgkmcnt(4)
	v_cvt_pk_bf16_f32 v5, v16, v18
	s_waitcnt lgkmcnt(2)
	v_cvt_pk_bf16_f32 v6, v20, v22
	s_waitcnt lgkmcnt(0)
	v_cvt_pk_bf16_f32 v7, v24, v26
	v_add_co_u32_e32 v8, vcc, 0xc000, v8
	global_store_dwordx4 v[10:11], v[4:7], off
	s_nop 0
	v_addc_co_u32_e32 v9, vcc, 0, v9, vcc
	v_cvt_pk_bf16_f32 v4, v15, v13
	v_cvt_pk_bf16_f32 v5, v17, v19
	v_cvt_pk_bf16_f32 v6, v21, v23
	v_cvt_pk_bf16_f32 v7, v25, v27
	global_store_dwordx4 v[8:9], v[4:7], off
	s_waitcnt lgkmcnt(0)

; #define LAS __attribute__((address_space(3)))
; __device__ __forceinline__ void tr_item(const float* W, int K, int N, bf16_t* WT, int ldt, int rowmode, const float* ksc, LAS float* scr, int item, int lane) {
;     const int nblk = N / 32, kb = item / nblk, nb = item % nblk, k0 = 64 * kb, n0 = 32 * nb;
; #pragma unroll 16
;     for (int i = 0; i < 32; ++i) { const int kk = 2 * i + (lane >> 5); float v = W[(size_t)(k0 + kk) * N + n0 + (lane & 31)]; if (ksc) v *= ksc[k0 + kk]; scr[kk * 33 + (lane & 31)] = v; }
.LBB0_123:
	global_load_dword v100, v[10:11], off
	v_add_u32_e32 v15, s9, v14
	v_add_u32_e32 v16, 6, v15
	v_mad_i64_i32 v[16:17], s[10:11], v16, s64, v[4:5]
	s_add_i32 s9, s9, 32
	v_lshl_add_u64 v[10:11], v[10:11], 0, s[16:17]
	s_cmp_lg_u32 s9, 64
	global_load_dword v101, v[8:9], off
	v_lshl_add_u64 v[8:9], v[8:9], 0, s[16:17]
	global_load_dword v102, v[6:7], off
	v_lshl_add_u64 v[6:7], v[6:7], 0, s[16:17]
	global_load_dword v103, v[16:17], off
	v_add_u32_e32 v16, 8, v15
	v_mad_i64_i32 v[16:17], s[10:11], v16, s64, v[4:5]
	global_load_dword v104, v[16:17], off
	v_add_u32_e32 v16, 10, v15
	v_mad_i64_i32 v[16:17], s[10:11], v16, s64, v[4:5]
	global_load_dword v105, v[16:17], off
	v_add_u32_e32 v16, 12, v15
	v_mad_i64_i32 v[16:17], s[10:11], v16, s64, v[4:5]
	global_load_dword v106, v[16:17], off
	v_add_u32_e32 v16, 14, v15
	v_mad_i64_i32 v[16:17], s[10:11], v16, s64, v[4:5]
	global_load_dword v107, v[16:17], off
	v_add_u32_e32 v16, 16, v15
	v_mad_i64_i32 v[16:17], s[10:11], v16, s64, v[4:5]
	global_load_dword v108, v[16:17], off
	v_add_u32_e32 v16, 18, v15
	v_mad_i64_i32 v[16:17], s[10:11], v16, s64, v[4:5]
	global_load_dword v109, v[16:17], off
	v_add_u32_e32 v16, 20, v15
	v_mad_i64_i32 v[16:17], s[10:11], v16, s64, v[4:5]
	global_load_dword v110, v[16:17], off
	v_add_u32_e32 v16, 22, v15
	v_mad_i64_i32 v[16:17], s[10:11], v16, s64, v[4:5]
	global_load_dword v111, v[16:17], off
	v_add_u32_e32 v16, 24, v15
	v_mad_i64_i32 v[16:17], s[10:11], v16, s64, v[4:5]
	global_load_dword v112, v[16:17], off
	v_add_u32_e32 v16, 26, v15
	v_mad_i64_i32 v[16:17], s[10:11], v16, s64, v[4:5]
	global_load_dword v113, v[16:17], off
	v_add_u32_e32 v16, 28, v15
	v_mad_i64_i32 v[16:17], s[10:11], v16, s64, v[4:5]
	v_add_u32_e32 v15, 30, v15
	global_load_dword v114, v[16:17], off
	v_mad_i64_i32 v[16:17], s[10:11], v15, s64, v[4:5]
	global_load_dword v115, v[16:17], off
	global_load_dword v116, v[10:11], off
	v_add_u32_e32 v15, s9, v14
	v_add_u32_e32 v16, 6, v15
	v_mad_i64_i32 v[16:17], s[10:11], v16, s64, v[4:5]
	s_add_i32 s9, s9, 32
	v_lshl_add_u64 v[10:11], v[10:11], 0, s[16:17]
	s_cmp_lg_u32 s9, 64
	global_load_dword v117, v[8:9], off
	v_lshl_add_u64 v[8:9], v[8:9], 0, s[16:17]
	global_load_dword v118, v[6:7], off
	v_lshl_add_u64 v[6:7], v[6:7], 0, s[16:17]
	global_load_dword v119, v[16:17], off
	v_add_u32_e32 v16, 8, v15
	v_mad_i64_i32 v[16:17], s[10:11], v16, s64, v[4:5]
	global_load_dword v120, v[16:17], off
	v_add_u32_e32 v16, 10, v15
	v_mad_i64_i32 v[16:17], s[10:11], v16, s64, v[4:5]
	global_load_dword v121, v[16:17], off
	v_add_u32_e32 v16, 12, v15
	v_mad_i64_i32 v[16:17], s[10:11], v16, s64, v[4:5]
	global_load_dword v122, v[16:17], off
	v_add_u32_e32 v16, 14, v15
	v_mad_i64_i32 v[16:17], s[10:11], v16, s64, v[4:5]
	global_load_dword v123, v[16:17], off
	v_add_u32_e32 v16, 16, v15
	v_mad_i64_i32 v[16:17], s[10:11], v16, s64, v[4:5]
	global_load_dword v124, v[16:17], off
	v_add_u32_e32 v16, 18, v15
	v_mad_i64_i32 v[16:17], s[10:11], v16, s64, v[4:5]
	global_load_dword v125, v[16:17], off
	v_add_u32_e32 v16, 20, v15
	v_mad_i64_i32 v[16:17], s[10:11], v16, s64, v[4:5]
	global_load_dword v126, v[16:17], off
	v_add_u32_e32 v16, 22, v15
	v_mad_i64_i32 v[16:17], s[10:11], v16, s64, v[4:5]
	global_load_dword v127, v[16:17], off
	v_add_u32_e32 v16, 24, v15
	v_mad_i64_i32 v[16:17], s[10:11], v16, s64, v[4:5]
	global_load_dword v128, v[16:17], off
	v_add_u32_e32 v16, 26, v15
	v_mad_i64_i32 v[16:17], s[10:11], v16, s64, v[4:5]
	global_load_dword v129, v[16:17], off
	v_add_u32_e32 v16, 28, v15
	v_mad_i64_i32 v[16:17], s[10:11], v16, s64, v[4:5]
	v_add_u32_e32 v15, 30, v15
	global_load_dword v130, v[16:17], off
	v_mad_i64_i32 v[16:17], s[10:11], v15, s64, v[4:5]
	global_load_dword v131, v[16:17], off
	s_waitcnt vmcnt(31)
	ds_write_b32 v13, v100
	s_waitcnt vmcnt(30)
	ds_write_b32 v13, v101 offset:264
	s_waitcnt vmcnt(29)
	ds_write_b32 v13, v102 offset:528
	s_waitcnt vmcnt(28)
	ds_write_b32 v13, v103 offset:792
	s_waitcnt vmcnt(27)
	ds_write_b32 v13, v104 offset:1056
	s_waitcnt vmcnt(26)
; #define LAS __attribute__((address_space(3)))
; __device__ __forceinline__ unsigned pk2(float lo, float hi) { f32x2 v = {lo, hi}; bf16x2_t b = __builtin_convertvector(v, bf16x2_t); return __builtin_bit_cast(unsigned, b); }
; __device__ __forceinline__ void tr_item(const float* W, int K, int N, bf16_t* WT, int ldt, int rowmode, const float* ksc, LAS float* scr, int item, int lane) {
;     ...
;     for (int i = 0; i < 32; ++i) { const int kk = 2 * i + (lane >> 5); float v = W[(size_t)(k0 + kk) * N + n0 + (lane & 31)]; if (ksc) v *= ksc[k0 + kk]; scr[kk * 33 + (lane & 31)] = v; }
;     asm volatile("s_waitcnt lgkmcnt(0)" ::: "memory");
;     const int c = lane & 7;
; #pragma unroll
;     for (int j = 0; j < 4; ++j) { const int n = n0 + (lane >> 3) + 8 * j; const LAS float* s = scr + (8 * c) * 33 + (lane >> 3) + 8 * j;
;         u32x4 o; o.x = pk2(s[0 * 33], s[1 * 33]); o.y = pk2(s[2 * 33], s[3 * 33]); o.z = pk2(s[4 * 33], s[5 * 33]); o.w = pk2(s[6 * 33], s[7 * 33]);
;         int row = n; if (rowmode) row = (n >> 7) * 256 + (n & 127) + (rowmode == 2 ? 128 : 0);
;         *(u32x4*)(WT + (size_t)row * ldt + k0 + 8 * c) = o; }
	ds_write_b32 v13, v105 offset:1320
	s_waitcnt vmcnt(25)
	ds_write_b32 v13, v106 offset:1584
	s_waitcnt vmcnt(24)
	ds_write_b32 v13, v107 offset:1848
	s_waitcnt vmcnt(23)
	ds_write_b32 v13, v108 offset:2112
	s_waitcnt vmcnt(22)
	ds_write_b32 v13, v109 offset:2376
	s_waitcnt vmcnt(21)
	ds_write_b32 v13, v110 offset:2640
	s_waitcnt vmcnt(20)
	ds_write_b32 v13, v111 offset:2904
	s_waitcnt vmcnt(19)
	ds_write_b32 v13, v112 offset:3168
	s_waitcnt vmcnt(18)
	ds_write_b32 v13, v113 offset:3432
	s_waitcnt vmcnt(17)
	ds_write_b32 v13, v114 offset:3696
	s_waitcnt vmcnt(16)
	ds_write_b32 v13, v115 offset:3960
	v_add_u32_e32 v13, 0x1080, v13
	s_waitcnt vmcnt(15)
	ds_write_b32 v13, v116
	s_waitcnt vmcnt(14)
	ds_write_b32 v13, v117 offset:264
	s_waitcnt vmcnt(13)
	ds_write_b32 v13, v118 offset:528
	s_waitcnt vmcnt(12)
	ds_write_b32 v13, v119 offset:792
	s_waitcnt vmcnt(11)
	ds_write_b32 v13, v120 offset:1056
	s_waitcnt vmcnt(10)
	ds_write_b32 v13, v121 offset:1320
	s_waitcnt vmcnt(9)
	ds_write_b32 v13, v122 offset:1584
	s_waitcnt vmcnt(8)
	ds_write_b32 v13, v123 offset:1848
	s_waitcnt vmcnt(7)
	ds_write_b32 v13, v124 offset:2112
	s_waitcnt vmcnt(6)
	ds_write_b32 v13, v125 offset:2376
	s_waitcnt vmcnt(5)
	ds_write_b32 v13, v126 offset:2640
	s_waitcnt vmcnt(4)
	ds_write_b32 v13, v127 offset:2904
	s_waitcnt vmcnt(3)
	ds_write_b32 v13, v128 offset:3168
	s_waitcnt vmcnt(2)
	ds_write_b32 v13, v129 offset:3432
	s_waitcnt vmcnt(1)
	ds_write_b32 v13, v130 offset:3696
	s_waitcnt vmcnt(0)
	ds_write_b32 v13, v131 offset:3960
	v_add_u32_e32 v13, 0x1080, v13
	v_lshlrev_b32_e32 v4, 3, v12
	v_ashrrev_i32_e32 v2, 3, v12
	v_and_b32_e32 v4, 56, v4
	v_add_u32_e32 v8, s8, v2
	v_mul_u32_u24_e32 v5, 0x84, v4
	v_lshlrev_b32_e32 v2, 2, v2
	s_waitcnt lgkmcnt(0)
	v_add3_u32 v28, s3, v5, v2
	ds_read2_b32 v[10:11], v28 offset0:33 offset1:41
	ds_read2_b32 v[12:13], v28 offset1:8
	ds_read2_b32 v[14:15], v28 offset0:66 offset1:74
	ds_read2_b32 v[16:17], v28 offset0:99 offset1:107
	ds_read2_b32 v[18:19], v28 offset0:132 offset1:140
	ds_read2_b32 v[20:21], v28 offset0:165 offset1:173
	ds_read2_b32 v[22:23], v28 offset0:198 offset1:206
	ds_read2_b32 v[24:25], v28 offset0:231 offset1:239
	s_lshl_b64 s[4:5], s[4:5], 1
	s_add_u32 s4, s23, s4
	s_addc_u32 s5, s24, s5
	v_lshlrev_b32_e32 v2, 1, v4
	v_ashrrev_i32_e32 v9, 31, v8
	v_lshl_add_u64 v[26:27], s[4:5], 0, v[2:3]
	v_lshlrev_b64 v[8:9], 11, v[8:9]
	s_waitcnt lgkmcnt(6)
	v_cvt_pk_bf16_f32 v4, v12, v10
	s_waitcnt lgkmcnt(4)
	v_cvt_pk_bf16_f32 v5, v14, v16
	s_waitcnt lgkmcnt(2)
	v_cvt_pk_bf16_f32 v6, v18, v20
	s_waitcnt lgkmcnt(0)
	v_cvt_pk_bf16_f32 v7, v22, v24
	v_lshl_add_u64 v[8:9], v[26:27], 0, v[8:9]
	global_store_dwordx4 v[8:9], v[4:7], off
	v_add_co_u32_e32 v10, vcc, s59, v8
	s_nop 0
	v_cvt_pk_bf16_f32 v4, v13, v11
	v_cvt_pk_bf16_f32 v5, v15, v17
	v_cvt_pk_bf16_f32 v6, v19, v21
	v_cvt_pk_bf16_f32 v7, v23, v25
	ds_read2_b32 v[12:13], v28 offset0:49 offset1:57
	ds_read2_b32 v[14:15], v28 offset0:16 offset1:24
	ds_read2_b32 v[16:17], v28 offset0:82 offset1:90
	ds_read2_b32 v[18:19], v28 offset0:115 offset1:123
	ds_read2_b32 v[20:21], v28 offset0:148 offset1:156
	ds_read2_b32 v[22:23], v28 offset0:181 offset1:189
	ds_read2_b32 v[24:25], v28 offset0:214 offset1:222
	ds_read2_b32 v[26:27], v28 offset0:247 offset1:255
	v_addc_co_u32_e32 v11, vcc, 0, v9, vcc
	global_store_dwordx4 v[10:11], v[4:7], off
	v_add_co_u32_e32 v10, vcc, s60, v8
	s_waitcnt lgkmcnt(6)
	v_cvt_pk_bf16_f32 v4, v14, v12
	v_addc_co_u32_e32 v11, vcc, 0, v9, vcc
	s_waitcnt lgkmcnt(4)
	v_cvt_pk_bf16_f32 v5, v16, v18
	s_waitcnt lgkmcnt(2)
	v_cvt_pk_bf16_f32 v6, v20, v22
	s_waitcnt lgkmcnt(0)
	v_cvt_pk_bf16_f32 v7, v24, v26
	v_add_co_u32_e32 v8, vcc, 0xc000, v8
	global_store_dwordx4 v[10:11], v[4:7], off
	s_nop 0
	v_addc_co_u32_e32 v9, vcc, 0, v9, vcc
	v_cvt_pk_bf16_f32 v4, v15, v13
	v_cvt_pk_bf16_f32 v5, v17, v19
	v_cvt_pk_bf16_f32 v6, v21, v23
	v_cvt_pk_bf16_f32 v7, v25, v27
	global_store_dwordx4 v[8:9], v[4:7], off
	s_waitcnt lgkmcnt(0)
	s_branch .LBB0_16
